# tile-granular split, loader poll without L1 invalidate
# baseline (speedup 1.0000x reference)
; #define SP_WAIT() asm volatile("s_waitcnt vmcnt(36)" ::: "memory")
; __device__ __forceinline__ void p3_rwkv_state(Frame& F, const Args& a) {
;     ...
;         for (int n = 0; n < NC; n += 2) {
;             if (n + SP_D + 1 < NC) { rw_dma_issue(P, lw, lane, lds0 + (unsigned)((n + SP_D) % SP_R) * SP_SLOT); rw_dma_issue(P, lw, lane, lds0 + (unsigned)((n + SP_D + 1) % SP_R) * SP_SLOT); SP_WAIT(); }
;             else asm volatile("s_waitcnt vmcnt(0)" ::: "memory");
.Lscan_ldbig_chk:
	s_lshr_b32 s24, s18, 1
	s_add_i32 s24, s24, 6
	s_cmp_lt_u32 s24, s17
	s_cbranch_scc1 .Lscan_ldbig_go
	v_add_u32_e32 v12, s17, v76
	v_lshlrev_b32_e32 v13, 2, v12
	v_add_u32_e32 v13, 0x8000, v13
	global_load_dword v13, v13, s[90:91] sc1
	s_movk_i32 s24, 0x1ff
	s_waitcnt vmcnt(0)
	v_cmp_ne_u32_e64 s[20:21], 0, v13
	v_cmp_lt_u32_e64 s[22:23], s24, v12
	s_nop 1
	s_or_b64 s[20:21], s[20:21], s[22:23]
	s_not_b64 s[20:21], s[20:21]
	s_ff1_i32_b64 s24, s[20:21]
	s_cmp_eq_u32 s24, -1
	s_cselect_b32 s24, 64, s24
	s_add_i32 s17, s17, s24
	s_cmp_lg_u32 s24, 0
	s_cbranch_scc1 .Lscan_ldbig_chk
	s_sleep 8
	s_branch .Lscan_ldbig_chk
